# phase 4 reordered: S5 pass A + context attention first, carry states published by counter; S5 pass C waits on the counter instead of a grid barrier
# speedup vs baseline: 1.0085x; 1.0085x over previous
.Lxbn2_end:
.LBB0_977:
	s_or_b64 exec, exec, s[4:5]
	s_mov_b64 s[20:21], s[0:1]
	v_mov_b32_e32 v133, v170
	s_waitcnt lgkmcnt(0)
	s_barrier
	s_load_dwordx2 s[4:5], s[20:21], 0x60
	v_and_b32_e32 v150, 63, v133
	v_lshlrev_b32_e32 v0, 2, v150
	s_waitcnt lgkmcnt(0)
	global_load_dword v1, v0, s[4:5]
	global_load_dword v2, v0, s[4:5] offset:256
	global_load_dword v3, v0, s[4:5] offset:512
	global_load_dword v4, v0, s[4:5] offset:768
	v_mbcnt_hi_u32_b32 v0, -1, v135
	v_and_b32_e32 v6, 64, v0
	v_xor_b32_e32 v5, 32, v0
	v_add_u32_e32 v6, 64, v6
	v_cmp_lt_i32_e32 vcc, v5, v6
	v_xor_b32_e32 v7, 16, v0
	v_xor_b32_e32 v8, 8, v0
	v_cndmask_b32_e32 v5, v0, v5, vcc
	v_lshlrev_b32_e32 v171, 2, v5
	v_cmp_lt_i32_e32 vcc, v7, v6
	v_xor_b32_e32 v9, 4, v0
	v_xor_b32_e32 v10, 2, v0
	v_cndmask_b32_e32 v7, v0, v7, vcc
	v_lshlrev_b32_e32 v172, 2, v7
	v_cmp_lt_i32_e32 vcc, v8, v6
	v_xor_b32_e32 v11, 1, v0
	s_mov_b32 s4, 0x3fb8aa3b
	s_mov_b32 s5, 0xc2ce8ed0
	s_mov_b32 s6, 0x42b17218
	s_waitcnt vmcnt(2)
	v_mul_f32_e32 v5, v1, v2
	ds_bpermute_b32 v5, v171, v5
	s_waitcnt vmcnt(0)
	v_mul_f32_e32 v12, v3, v4
	ds_bpermute_b32 v12, v171, v12
	s_waitcnt lgkmcnt(1)
	v_fmac_f32_e32 v5, v1, v2
	ds_bpermute_b32 v1, v172, v5
	s_waitcnt lgkmcnt(1)
	v_fmac_f32_e32 v12, v3, v4
	ds_bpermute_b32 v2, v172, v12
	v_cndmask_b32_e32 v3, v0, v8, vcc
	v_lshlrev_b32_e32 v173, 2, v3
	s_waitcnt lgkmcnt(1)
	v_add_f32_e32 v1, v5, v1
	ds_bpermute_b32 v3, v173, v1
	s_waitcnt lgkmcnt(1)
	v_add_f32_e32 v2, v12, v2
	ds_bpermute_b32 v4, v173, v2
	v_cmp_lt_i32_e32 vcc, v9, v6
	s_waitcnt lgkmcnt(1)
	v_add_f32_e32 v1, v1, v3
	v_cndmask_b32_e32 v5, v0, v9, vcc
	v_lshlrev_b32_e32 v174, 2, v5
	s_waitcnt lgkmcnt(0)
	v_add_f32_e32 v2, v2, v4
	ds_bpermute_b32 v3, v174, v1
	ds_bpermute_b32 v4, v174, v2
	v_cmp_lt_i32_e32 vcc, v10, v6
	s_waitcnt lgkmcnt(1)
	v_add_f32_e32 v1, v1, v3
	v_cndmask_b32_e32 v5, v0, v10, vcc
	v_lshlrev_b32_e32 v175, 2, v5
	s_waitcnt lgkmcnt(0)
	v_add_f32_e32 v2, v2, v4
	ds_bpermute_b32 v3, v175, v1
	ds_bpermute_b32 v4, v175, v2
	v_cmp_lt_i32_e32 vcc, v11, v6
	s_nop 1
	v_cndmask_b32_e32 v0, v0, v11, vcc
	v_lshlrev_b32_e32 v176, 2, v0
	s_waitcnt lgkmcnt(1)
	v_add_f32_e32 v0, v1, v3
	s_waitcnt lgkmcnt(0)
	v_add_f32_e32 v1, v2, v4
	ds_bpermute_b32 v2, v176, v0
	ds_bpermute_b32 v3, v176, v1
	v_mov_b32_e32 v4, 0x7f800000
	s_waitcnt lgkmcnt(1)
	v_add_f32_e32 v0, v0, v2
	s_waitcnt lgkmcnt(0)
	v_add_f32_e32 v1, v1, v3
	v_mul_f32_e32 v2, 0x3fb8aa3b, v0
	v_mul_f32_e32 v3, 0x3fb8aa3b, v1
	v_fma_f32 v5, v0, s4, -v2
	v_rndne_f32_e32 v6, v2
	v_fma_f32 v7, v1, s4, -v3
	v_rndne_f32_e32 v8, v3
	v_fmac_f32_e32 v5, 0x32a5705f, v0
	v_sub_f32_e32 v2, v2, v6
	v_fmac_f32_e32 v7, 0x32a5705f, v1
	v_sub_f32_e32 v3, v3, v8
	v_add_f32_e32 v2, v2, v5
	v_cvt_i32_f32_e32 v6, v6
	v_add_f32_e32 v3, v3, v7
	v_exp_f32_e32 v2, v2
	v_cvt_i32_f32_e32 v8, v8
	v_exp_f32_e32 v3, v3
	v_cmp_ngt_f32_e32 vcc, s5, v0
	v_ldexp_f32 v2, v2, v6
	s_and_b32 s4, s42, 7
	v_ldexp_f32 v3, v3, v8
	v_cndmask_b32_e32 v2, 0, v2, vcc
	v_cmp_ngt_f32_e32 vcc, s5, v1
	s_cmp_lg_u32 s4, 0
	s_mov_b32 s5, s2
	v_cndmask_b32_e32 v3, 0, v3, vcc
	v_cmp_nlt_f32_e32 vcc, s6, v0
	s_nop 1
	v_cndmask_b32_e32 v0, v4, v2, vcc
	v_cmp_nlt_f32_e32 vcc, s6, v1
	s_nop 1
	v_cndmask_b32_e32 v1, v4, v3, vcc
	v_sub_f32_e32 v0, v0, v1
	s_nop 0
	v_readfirstlane_b32 s4, v0
	v_mov_b32_e32 v0, 0x3e4ccccd
	v_add_f32_e32 v166, s4, v0
	s_branch .LBB0_1001
.Lp4_mid:
	s_waitcnt vmcnt(0) lgkmcnt(0)
	s_barrier
	s_and_saveexec_b64 s[4:5], s[38:39]
	s_cbranch_execz .Lp4_mid2
	s_load_dwordx2 s[6:7], s[0:1], 0xe8
	v_mov_b32_e32 v0, 0
	v_mov_b32_e32 v1, 1
	s_waitcnt lgkmcnt(0)
	s_add_u32 s6, s6, 0x779be00
	s_addc_u32 s7, s7, 0
	global_atomic_add v0, v1, s[6:7]
.Lp4_mid2:
	s_or_b64 exec, exec, s[4:5]
	v_mov_b32_e32 v133, v170
	v_and_b32_e32 v150, 63, v133
	s_and_b32 s5, s2, 7
	s_ashr_i32 s6, s42, 3
	s_mul_i32 s5, s6, s5
	s_lshr_b32 s6, s2, 3
	s_add_i32 s5, s5, s6

.LBB0_1021:
	v_add_u32_e32 v57, s57, v169
	ds_read_u16_d16_hi v58, v57 offset:128
	ds_read_u16_d16_hi v59, v57 offset:0
	ds_read_u16_d16_hi v68, v57 offset:400
	ds_read_u16_d16_hi v69, v57 offset:272
	ds_read_u16_d16_hi v70, v57 offset:672
	ds_read_u16_d16_hi v71, v57 offset:544
	ds_read_u16_d16_hi v72, v57 offset:944
	ds_read_u16_d16_hi v73, v57 offset:816
	ds_read_u16_d16_hi v74, v57 offset:1216
	ds_read_u16_d16_hi v75, v57 offset:1088
	ds_read_u16_d16_hi v76, v57 offset:1488
	ds_read_u16_d16_hi v77, v57 offset:1360
	ds_read_u16_d16_hi v78, v57 offset:1760
	ds_read_u16_d16_hi v79, v57 offset:1632
	ds_read_u16_d16_hi v80, v57 offset:2032
	ds_read_u16_d16_hi v81, v57 offset:1904
	ds_read_u16_d16_hi v82, v57 offset:2304
	ds_read_u16_d16_hi v83, v57 offset:2176
	ds_read_u16_d16_hi v84, v57 offset:2576
	ds_read_u16_d16_hi v85, v57 offset:2448
	ds_read_u16_d16_hi v86, v57 offset:2848
	ds_read_u16_d16_hi v87, v57 offset:2720
	ds_read_u16_d16_hi v88, v57 offset:3120
	ds_read_u16_d16_hi v89, v57 offset:2992
	ds_read_u16_d16_hi v90, v57 offset:3392
	ds_read_u16_d16_hi v91, v57 offset:3264
	ds_read_u16_d16_hi v92, v57 offset:3664
	ds_read_u16_d16_hi v93, v57 offset:3536
	ds_read_u16_d16_hi v94, v57 offset:3936
	ds_read_u16_d16_hi v95, v57 offset:3808
	ds_read_u16_d16_hi v96, v57 offset:4208
	ds_read_u16_d16_hi v97, v57 offset:4080
	s_waitcnt lgkmcnt(15)
	v_pk_fma_f32 v[58:59], v[50:51], v[62:63], v[58:59]
	v_pk_fma_f32 v[62:63], v[48:49], v[62:63], v[58:59] op_sel:[0,1,0] op_sel_hi:[1,0,1]
	s_waitcnt lgkmcnt(15)
	v_pk_fma_f32 v[68:69], v[50:51], v[62:63], v[68:69]
	v_pk_fma_f32 v[62:63], v[48:49], v[62:63], v[68:69] op_sel:[0,1,0] op_sel_hi:[1,0,1]
	s_waitcnt lgkmcnt(15)
	v_pk_fma_f32 v[70:71], v[50:51], v[62:63], v[70:71]
	v_pk_fma_f32 v[62:63], v[48:49], v[62:63], v[70:71] op_sel:[0,1,0] op_sel_hi:[1,0,1]
	s_waitcnt lgkmcnt(15)
	v_pk_fma_f32 v[72:73], v[50:51], v[62:63], v[72:73]
	v_pk_fma_f32 v[62:63], v[48:49], v[62:63], v[72:73] op_sel:[0,1,0] op_sel_hi:[1,0,1]
	s_waitcnt lgkmcnt(15)
	v_pk_fma_f32 v[74:75], v[50:51], v[62:63], v[74:75]
	v_pk_fma_f32 v[62:63], v[48:49], v[62:63], v[74:75] op_sel:[0,1,0] op_sel_hi:[1,0,1]
	s_waitcnt lgkmcnt(15)
	v_pk_fma_f32 v[76:77], v[50:51], v[62:63], v[76:77]
	v_pk_fma_f32 v[62:63], v[48:49], v[62:63], v[76:77] op_sel:[0,1,0] op_sel_hi:[1,0,1]
	s_waitcnt lgkmcnt(15)
	v_pk_fma_f32 v[78:79], v[50:51], v[62:63], v[78:79]
	v_pk_fma_f32 v[62:63], v[48:49], v[62:63], v[78:79] op_sel:[0,1,0] op_sel_hi:[1,0,1]
	s_waitcnt lgkmcnt(15)
	v_pk_fma_f32 v[80:81], v[50:51], v[62:63], v[80:81]
	v_pk_fma_f32 v[62:63], v[48:49], v[62:63], v[80:81] op_sel:[0,1,0] op_sel_hi:[1,0,1]
	s_waitcnt lgkmcnt(14)
	v_pk_fma_f32 v[82:83], v[50:51], v[62:63], v[82:83]
	v_pk_fma_f32 v[62:63], v[48:49], v[62:63], v[82:83] op_sel:[0,1,0] op_sel_hi:[1,0,1]
	s_waitcnt lgkmcnt(12)
	v_pk_fma_f32 v[84:85], v[50:51], v[62:63], v[84:85]
	v_pk_fma_f32 v[62:63], v[48:49], v[62:63], v[84:85] op_sel:[0,1,0] op_sel_hi:[1,0,1]
	s_waitcnt lgkmcnt(10)
	v_pk_fma_f32 v[86:87], v[50:51], v[62:63], v[86:87]
	v_pk_fma_f32 v[62:63], v[48:49], v[62:63], v[86:87] op_sel:[0,1,0] op_sel_hi:[1,0,1]
	s_waitcnt lgkmcnt(8)
	v_pk_fma_f32 v[88:89], v[50:51], v[62:63], v[88:89]
	v_pk_fma_f32 v[62:63], v[48:49], v[62:63], v[88:89] op_sel:[0,1,0] op_sel_hi:[1,0,1]
	s_waitcnt lgkmcnt(6)
	v_pk_fma_f32 v[90:91], v[50:51], v[62:63], v[90:91]
	v_pk_fma_f32 v[62:63], v[48:49], v[62:63], v[90:91] op_sel:[0,1,0] op_sel_hi:[1,0,1]
	s_waitcnt lgkmcnt(4)
	v_pk_fma_f32 v[92:93], v[50:51], v[62:63], v[92:93]
	v_pk_fma_f32 v[62:63], v[48:49], v[62:63], v[92:93] op_sel:[0,1,0] op_sel_hi:[1,0,1]
	s_waitcnt lgkmcnt(2)
	v_pk_fma_f32 v[94:95], v[50:51], v[62:63], v[94:95]
	v_pk_fma_f32 v[62:63], v[48:49], v[62:63], v[94:95] op_sel:[0,1,0] op_sel_hi:[1,0,1]
	s_waitcnt lgkmcnt(0)
	v_pk_fma_f32 v[96:97], v[50:51], v[62:63], v[96:97]
	v_pk_fma_f32 v[62:63], v[48:49], v[62:63], v[96:97] op_sel:[0,1,0] op_sel_hi:[1,0,1]
	s_addk_i32 s57, 0x1100
	s_cmpk_eq_i32 s57, 0x4400
	s_cbranch_scc0 .LBB0_1021
	s_lshl_b32 s8, s56, 8
	s_lshl_b32 s33, s37, 7
	s_or_b32 s8, s33, s8
	s_waitcnt vmcnt(7)
	v_mfma_f32_16x16x32_bf16 v[50:53], v[44:47], v[12:15], 0
	v_or_b32_e32 v48, s8, v167
	v_mov_b32_e32 v49, v145
	v_lshl_add_u64 v[54:55], v[48:49], 2, s[30:31]
	s_waitcnt vmcnt(6)
	v_mfma_f32_16x16x32_bf16 v[68:71], v[40:43], v[12:15], 0
	v_lshl_add_u64 v[48:49], v[54:55], 0, s[22:23]
	v_add_co_u32_e32 v54, vcc, 0xb79c000, v54
	s_waitcnt vmcnt(5)
	v_mfma_f32_16x16x32_bf16 v[72:75], v[36:39], v[12:15], 0
	v_pk_mov_b32 v[58:59], v[62:63], v[62:63] op_sel:[1,0]
	v_addc_co_u32_e32 v55, vcc, 0, v55, vcc
	s_waitcnt vmcnt(4)
	v_mfma_f32_16x16x32_bf16 v[76:79], v[32:35], v[12:15], 0
	global_store_dwordx2 v[54:55], v[58:59], off sc1
	v_cvt_pk_bf16_f32 v54, v50, v51
	v_cvt_pk_bf16_f32 v55, v52, v53
	s_waitcnt vmcnt(4)
	v_mfma_f32_16x16x32_bf16 v[62:65], v[28:31], v[12:15], 0
	v_cvt_pk_bf16_f32 v58, v68, v69
	v_cvt_pk_bf16_f32 v59, v70, v71
	s_waitcnt lgkmcnt(0)
	s_waitcnt vmcnt(3)
	v_mfma_f32_16x16x32_bf16 v[80:83], v[24:27], v[12:15], 0
	ds_write2_b64 v179, v[54:55], v[58:59] offset1:4
	v_cvt_pk_bf16_f32 v54, v72, v73
	v_cvt_pk_bf16_f32 v55, v74, v75
	s_waitcnt vmcnt(2)
	v_mfma_f32_16x16x32_bf16 v[50:53], v[20:23], v[12:15], 0
	v_cvt_pk_bf16_f32 v58, v76, v77
	v_cvt_pk_bf16_f32 v59, v78, v79
	ds_write2_b64 v179, v[54:55], v[58:59] offset0:8 offset1:12
	s_waitcnt vmcnt(1)
	v_mfma_f32_16x16x32_bf16 v[12:15], v[16:19], v[12:15], 0
	v_cvt_pk_bf16_f32 v54, v62, v63
	v_cvt_pk_bf16_f32 v55, v64, v65
	v_cvt_pk_bf16_f32 v58, v80, v81
	v_mfma_f32_16x16x32_bf16 v[68:71], v[44:47], v[4:7], 0
	v_cvt_pk_bf16_f32 v59, v82, v83
	ds_write2_b64 v179, v[54:55], v[58:59] offset0:16 offset1:20
	v_cvt_pk_bf16_f32 v54, v50, v51
	v_mfma_f32_16x16x32_bf16 v[72:75], v[40:43], v[4:7], 0
	v_cvt_pk_bf16_f32 v55, v52, v53
	v_cvt_pk_bf16_f32 v12, v12, v13
	v_cvt_pk_bf16_f32 v13, v14, v15
	v_mfma_f32_16x16x32_bf16 v[62:65], v[36:39], v[4:7], 0
	ds_write2_b64 v179, v[54:55], v[12:13] offset0:24 offset1:28
	v_cvt_pk_bf16_f32 v54, v68, v69
	v_cvt_pk_bf16_f32 v55, v70, v71
	v_mfma_f32_16x16x32_bf16 v[50:53], v[32:35], v[4:7], 0
	v_cvt_pk_bf16_f32 v58, v72, v73
	v_cvt_pk_bf16_f32 v59, v74, v75
	ds_write2_b64 v66, v[54:55], v[58:59] offset0:32 offset1:36
	v_mfma_f32_16x16x32_bf16 v[12:15], v[28:31], v[4:7], 0
	v_cvt_pk_bf16_f32 v54, v62, v63
	v_cvt_pk_bf16_f32 v55, v64, v65
	s_nop 1
	v_cvt_pk_bf16_f32 v50, v50, v51
	v_mfma_f32_16x16x32_bf16 v[68:71], v[24:27], v[4:7], 0
	v_cvt_pk_bf16_f32 v51, v52, v53
	ds_write2_b64 v66, v[54:55], v[50:51] offset0:40 offset1:44
	v_cvt_pk_bf16_f32 v50, v12, v13
	v_mfma_f32_16x16x32_bf16 v[72:75], v[20:23], v[4:7], 0
	v_cvt_pk_bf16_f32 v51, v14, v15
	s_nop 2
	v_cvt_pk_bf16_f32 v52, v68, v69
	v_cvt_pk_bf16_f32 v53, v70, v71
	v_mfma_f32_16x16x32_bf16 v[4:7], v[16:19], v[4:7], 0
	ds_write2_b64 v66, v[50:51], v[52:53] offset0:48 offset1:52
	v_cvt_pk_bf16_f32 v54, v72, v73
	v_cvt_pk_bf16_f32 v55, v74, v75
	v_mfma_f32_16x16x32_bf16 v[12:15], v[44:47], v[8:11], 0
	s_movk_i32 s8, 0x3300
	s_nop 2
	v_cvt_pk_bf16_f32 v4, v4, v5
	v_cvt_pk_bf16_f32 v5, v6, v7
	v_mfma_f32_16x16x32_bf16 v[50:53], v[40:43], v[8:11], 0
	ds_write2_b64 v66, v[54:55], v[4:5] offset0:56 offset1:60
	v_cvt_pk_bf16_f32 v54, v12, v13
	v_cvt_pk_bf16_f32 v55, v14, v15
	v_mfma_f32_16x16x32_bf16 v[62:65], v[36:39], v[8:11], 0
	v_mfma_f32_16x16x32_bf16 v[4:7], v[32:35], v[8:11], 0
	s_nop 2
	v_cvt_pk_bf16_f32 v50, v50, v51
	v_cvt_pk_bf16_f32 v51, v52, v53
	ds_write2_b64 v67, v[54:55], v[50:51] offset0:64 offset1:68
	v_mfma_f32_16x16x32_bf16 v[12:15], v[28:31], v[8:11], 0
	v_cvt_pk_bf16_f32 v54, v62, v63
	v_cvt_pk_bf16_f32 v55, v64, v65
	v_cvt_pk_bf16_f32 v4, v4, v5
	v_mfma_f32_16x16x32_bf16 v[50:53], v[24:27], v[8:11], 0
	v_cvt_pk_bf16_f32 v5, v6, v7
	ds_write2_b64 v67, v[54:55], v[4:5] offset0:72 offset1:76
	s_nop 1
	v_cvt_pk_bf16_f32 v12, v12, v13
	v_mfma_f32_16x16x32_bf16 v[4:7], v[20:23], v[8:11], 0
	v_cvt_pk_bf16_f32 v13, v14, v15
	s_nop 0
	v_cvt_pk_bf16_f32 v14, v50, v51
	v_cvt_pk_bf16_f32 v15, v52, v53
	v_mfma_f32_16x16x32_bf16 v[8:11], v[16:19], v[8:11], 0
	ds_write2_b64 v67, v[12:13], v[14:15] offset0:80 offset1:84
	s_nop 1
	v_cvt_pk_bf16_f32 v50, v4, v5
	v_cvt_pk_bf16_f32 v51, v6, v7
	v_mfma_f32_16x16x32_bf16 v[12:15], v[44:47], v[0:3], 0
	v_mfma_f32_16x16x32_bf16 v[4:7], v[40:43], v[0:3], 0
	s_nop 0
	v_cvt_pk_bf16_f32 v8, v8, v9
	v_cvt_pk_bf16_f32 v9, v10, v11
	s_nop 3
	v_cvt_pk_bf16_f32 v12, v12, v13
	v_cvt_pk_bf16_f32 v13, v14, v15
	ds_write2_b64 v67, v[50:51], v[8:9] offset0:88 offset1:92
	v_cvt_pk_bf16_f32 v4, v4, v5
	v_cvt_pk_bf16_f32 v5, v6, v7
	v_mfma_f32_16x16x32_bf16 v[8:11], v[36:39], v[0:3], 0
	ds_write2_b64 v56, v[12:13], v[4:5] offset0:96 offset1:100
	v_mfma_f32_16x16x32_bf16 v[4:7], v[32:35], v[0:3], 0
	s_nop 5
	v_cvt_pk_bf16_f32 v12, v8, v9
	v_cvt_pk_bf16_f32 v13, v10, v11
	v_cvt_pk_bf16_f32 v4, v4, v5
	v_cvt_pk_bf16_f32 v5, v6, v7
	v_mfma_f32_16x16x32_bf16 v[8:11], v[28:31], v[0:3], 0
	ds_write2_b64 v56, v[12:13], v[4:5] offset0:104 offset1:108
	v_mfma_f32_16x16x32_bf16 v[4:7], v[24:27], v[0:3], 0
	s_nop 5
	v_cvt_pk_bf16_f32 v8, v8, v9
	v_cvt_pk_bf16_f32 v9, v10, v11
	v_cvt_pk_bf16_f32 v10, v4, v5
	v_cvt_pk_bf16_f32 v11, v6, v7
	v_mfma_f32_16x16x32_bf16 v[4:7], v[20:23], v[0:3], 0
	ds_write2_b64 v56, v[8:9], v[10:11] offset0:112 offset1:116
	v_mov_b32_e32 v8, 0
	v_mov_b32_e32 v9, v8
	v_mfma_f32_16x16x32_bf16 v[0:3], v[16:19], v[0:3], 0
	s_nop 3
	v_cvt_pk_bf16_f32 v4, v4, v5
	v_cvt_pk_bf16_f32 v5, v6, v7
	s_nop 1
	v_cvt_pk_bf16_f32 v0, v0, v1
	v_cvt_pk_bf16_f32 v1, v2, v3
	ds_write2_b64 v56, v[4:5], v[0:1] offset0:120 offset1:124
	s_waitcnt lgkmcnt(0)
	v_xor_b32_e32 v1, 0x80000000, v61
	v_mov_b32_e32 v0, v61
	v_mov_b32_e32 v2, v60
	v_mov_b32_e32 v3, v60
	v_mov_b32_e32 v60, v1
	v_pk_mov_b32 v[4:5], v[0:1], v[0:1] op_sel:[1,0]
	v_pk_mov_b32 v[6:7], v[60:61], v[60:61] op_sel:[1,0]
.LBB0_1023:
	v_add_u32_e32 v10, s8, v169
	ds_read_u16_d16_hi v12, v10 offset:4208
	ds_read_u16_d16_hi v13, v10 offset:4080
	ds_read_u16_d16_hi v14, v10 offset:3936
	ds_read_u16_d16_hi v15, v10 offset:3808
	ds_read_u16_d16_hi v16, v10 offset:3664
	ds_read_u16_d16_hi v17, v10 offset:3536
	ds_read_u16_d16_hi v18, v10 offset:3392
	ds_read_u16_d16_hi v19, v10 offset:3264
	ds_read_u16_d16_hi v20, v10 offset:3120
	ds_read_u16_d16_hi v21, v10 offset:2992
	ds_read_u16_d16_hi v22, v10 offset:2848
	ds_read_u16_d16_hi v23, v10 offset:2720
	ds_read_u16_d16_hi v24, v10 offset:2576
	ds_read_u16_d16_hi v25, v10 offset:2448
	ds_read_u16_d16_hi v26, v10 offset:2304
	ds_read_u16_d16_hi v27, v10 offset:2176
	ds_read_u16_d16_hi v28, v10 offset:2032
	ds_read_u16_d16_hi v29, v10 offset:1904
	ds_read_u16_d16_hi v30, v10 offset:1760
	ds_read_u16_d16_hi v31, v10 offset:1632
	ds_read_u16_d16_hi v32, v10 offset:1488
	ds_read_u16_d16_hi v33, v10 offset:1360
	ds_read_u16_d16_hi v34, v10 offset:1216
	ds_read_u16_d16_hi v35, v10 offset:1088
	ds_read_u16_d16_hi v36, v10 offset:944
	ds_read_u16_d16_hi v37, v10 offset:816
	ds_read_u16_d16_hi v38, v10 offset:672
	ds_read_u16_d16_hi v39, v10 offset:544
	ds_read_u16_d16_hi v40, v10 offset:400
	ds_read_u16_d16_hi v41, v10 offset:272
	ds_read_u16_d16_hi v11, v10 offset:0
	ds_read_u16_d16_hi v10, v10 offset:128
	s_waitcnt lgkmcnt(15)
	v_pk_fma_f32 v[12:13], v[2:3], v[8:9], v[12:13]
	v_pk_fma_f32 v[8:9], v[0:1], v[8:9], v[12:13] op_sel:[0,1,0] op_sel_hi:[1,0,1]
	s_waitcnt lgkmcnt(15)
	v_pk_fma_f32 v[14:15], v[2:3], v[8:9], v[14:15]
	v_pk_fma_f32 v[8:9], v[0:1], v[8:9], v[14:15] op_sel:[0,1,0] op_sel_hi:[1,0,1]
	s_waitcnt lgkmcnt(15)
	v_pk_fma_f32 v[16:17], v[2:3], v[8:9], v[16:17]
	v_pk_fma_f32 v[8:9], v[0:1], v[8:9], v[16:17] op_sel:[0,1,0] op_sel_hi:[1,0,1]
	s_waitcnt lgkmcnt(15)
	v_pk_fma_f32 v[18:19], v[2:3], v[8:9], v[18:19]
	v_pk_fma_f32 v[8:9], v[0:1], v[8:9], v[18:19] op_sel:[0,1,0] op_sel_hi:[1,0,1]
	s_waitcnt lgkmcnt(15)
	v_pk_fma_f32 v[20:21], v[2:3], v[8:9], v[20:21]
	v_pk_fma_f32 v[8:9], v[0:1], v[8:9], v[20:21] op_sel:[0,1,0] op_sel_hi:[1,0,1]
	s_waitcnt lgkmcnt(15)
	v_pk_fma_f32 v[22:23], v[2:3], v[8:9], v[22:23]
	v_pk_fma_f32 v[8:9], v[0:1], v[8:9], v[22:23] op_sel:[0,1,0] op_sel_hi:[1,0,1]
	s_waitcnt lgkmcnt(15)
	v_pk_fma_f32 v[24:25], v[2:3], v[8:9], v[24:25]
	v_pk_fma_f32 v[8:9], v[0:1], v[8:9], v[24:25] op_sel:[0,1,0] op_sel_hi:[1,0,1]
	s_waitcnt lgkmcnt(15)
	v_pk_fma_f32 v[26:27], v[2:3], v[8:9], v[26:27]
	v_pk_fma_f32 v[8:9], v[0:1], v[8:9], v[26:27] op_sel:[0,1,0] op_sel_hi:[1,0,1]
	s_waitcnt lgkmcnt(14)
	v_pk_fma_f32 v[28:29], v[2:3], v[8:9], v[28:29]
	v_pk_fma_f32 v[8:9], v[0:1], v[8:9], v[28:29] op_sel:[0,1,0] op_sel_hi:[1,0,1]
	s_waitcnt lgkmcnt(12)
	v_pk_fma_f32 v[30:31], v[2:3], v[8:9], v[30:31]
	v_pk_fma_f32 v[8:9], v[0:1], v[8:9], v[30:31] op_sel:[0,1,0] op_sel_hi:[1,0,1]
	s_waitcnt lgkmcnt(10)
	v_pk_fma_f32 v[32:33], v[2:3], v[8:9], v[32:33]
	v_pk_fma_f32 v[8:9], v[0:1], v[8:9], v[32:33] op_sel:[0,1,0] op_sel_hi:[1,0,1]
	s_waitcnt lgkmcnt(8)
	v_pk_fma_f32 v[34:35], v[2:3], v[8:9], v[34:35]
	v_pk_fma_f32 v[8:9], v[0:1], v[8:9], v[34:35] op_sel:[0,1,0] op_sel_hi:[1,0,1]
	s_waitcnt lgkmcnt(6)
	v_pk_fma_f32 v[36:37], v[2:3], v[8:9], v[36:37]
	v_pk_fma_f32 v[8:9], v[0:1], v[8:9], v[36:37] op_sel:[0,1,0] op_sel_hi:[1,0,1]
	s_waitcnt lgkmcnt(4)
	v_pk_fma_f32 v[38:39], v[2:3], v[8:9], v[38:39]
	v_pk_fma_f32 v[8:9], v[0:1], v[8:9], v[38:39] op_sel:[0,1,0] op_sel_hi:[1,0,1]
	s_waitcnt lgkmcnt(2)
	v_pk_fma_f32 v[40:41], v[2:3], v[8:9], v[40:41]
	v_pk_fma_f32 v[8:9], v[0:1], v[8:9], v[40:41] op_sel:[0,1,0] op_sel_hi:[1,0,1]
	s_waitcnt lgkmcnt(0)
	v_pk_fma_f32 v[10:11], v[2:3], v[8:9], v[10:11]
	v_pk_fma_f32 v[8:9], v[0:1], v[8:9], v[10:11] op_sel:[0,1,0] op_sel_hi:[1,0,1]
	s_addk_i32 s8, 0xef00
	s_cmpk_eq_i32 s8, 0xef00
	s_cbranch_scc0 .LBB0_1023
	v_pk_mov_b32 v[0:1], v[8:9], v[8:9] op_sel:[1,0]
	s_mov_b64 s[30:31], 0
	global_store_dwordx2 v[48:49], v[0:1], off offset:512 sc1

.LBB0_1031:
	s_mov_b64 s[6:7], s[0:1]
	s_getreg_b32 s8, hwreg(HW_REG_XCC_ID, 0, 4)
	s_waitcnt vmcnt(0)
	s_barrier
	s_and_saveexec_b64 s[4:5], s[38:39]
	s_cbranch_execz .LBB0_1083
	s_load_dwordx2 s[18:19], s[0:1], 0xe8
	v_mov_b32_e32 v0, 0
	s_mov_b32 s22, 0
	s_waitcnt lgkmcnt(0)
	s_add_u32 s18, s18, 0x779be00
	s_addc_u32 s19, s19, 0
.Lp4_w:
	global_load_dword v2, v0, s[18:19] sc1
	s_waitcnt vmcnt(0)
	v_readfirstlane_b32 s23, v2
	s_cmpk_ge_u32 s23, 0x100
	s_cbranch_scc1 .Lp4_w_ok
	s_sleep 1
	s_add_i32 s22, s22, 1
	s_cmp_lt_u32 s22, 0x40000
	s_cbranch_scc1 .Lp4_w
.Lp4_w_ok:
	buffer_inv sc1
.LBB0_1083:
	s_or_b64 exec, exec, s[4:5]
	s_mov_b64 s[52:53], s[0:1]
	s_waitcnt lgkmcnt(0)
	v_mov_b32_e32 v0, v170
	s_barrier
	s_movk_i32 s4, 0x1800
	v_ashrrev_i32_e32 v1, 6, v0
	v_add_u32_e32 v133, s46, v1
	v_cmp_gt_i32_e32 vcc, s4, v133
	s_and_saveexec_b64 s[54:55], vcc
	s_cbranch_execz .LBB0_1118
	s_load_dwordx2 s[6:7], s[52:53], 0xe8
	v_and_b32_e32 v4, 63, v0
	v_mov_b32_e32 v121, 0
	s_movk_i32 s4, 0x4400
	v_lshlrev_b32_e32 v122, 4, v4
	s_waitcnt lgkmcnt(0)
	s_add_u32 s56, s6, 0x9f9c000
	v_mov_b32_e32 v123, v121
	v_bfe_u32 v5, v0, 4, 2
	v_mul_lo_u32 v1, v1, s4
	s_addc_u32 s57, s7, 0
	v_lshl_add_u64 v[2:3], s[6:7], 0, v[122:123]
	s_mov_b64 s[8:9], 0x76d8000
	v_lshrrev_b32_e32 v6, 6, v0
	v_and_b32_e32 v177, 15, v0
	v_add_u32_e32 v1, 0, v1
	v_lshlrev_b32_e32 v120, 3, v5
	s_add_u32 s58, s6, 0x76c8000
	v_lshl_add_u64 v[124:125], v[2:3], 0, s[8:9]
	s_mov_b64 s[8:9], 0x7758000
	v_lshlrev_b32_e32 v128, 3, v4
	v_mov_b32_e32 v129, v121
	v_and_b32_e32 v0, 48, v0
	v_cmp_gt_u32_e64 s[4:5], 32, v4
	s_addc_u32 s59, s7, 0
	v_lshl_add_u64 v[126:127], v[2:3], 0, s[8:9]
	v_lshl_add_u64 v[2:3], s[6:7], 0, v[128:129]
	v_lshlrev_b32_e32 v132, 1, v4
	v_add_u32_e32 v8, v1, v0
	v_lshlrev_b32_e32 v0, 2, v5
	v_lshl_add_u64 v[4:5], s[6:7], 0, v[120:121]
	s_mov_b64 s[6:7], 0xbd9c000
	s_mov_b64 s[8:9], 0xb79c000
	v_add_u32_e32 v7, v1, v120
	v_mul_u32_u24_e32 v9, 0x110, v177
	v_lshl_add_u64 v[134:135], v[4:5], 0, s[6:7]
	s_mov_b64 s[6:7], 0xb79c200
	s_mov_b32 s64, 0xfff80000
	v_lshl_add_u64 v[130:131], v[2:3], 0, s[8:9]
	v_add_u32_e32 v123, v1, v132
	v_add_u16_e32 v178, s46, v6
	v_lshl_add_u64 v[136:137], v[2:3], 0, s[6:7]
	s_mov_b64 s[60:61], 0
	v_lshlrev_b32_e32 v138, 2, v120
	s_movk_i32 s45, 0x1000
	s_mov_b64 s[62:63], 0x80000
	s_mov_b32 s65, -1
	v_lshlrev_b32_e32 v140, 2, v0
	s_movk_i32 s47, 0x17ff
	v_mov_b32_e32 v139, v121
	v_add_u32_e32 v179, v7, v9
	v_add_u32_e32 v180, v8, v9
	s_branch .LBB0_1086
